# att10 = att7 + 96 dead zero-initialising v_mov removed in front of full-row-rotate DPP moves in the up-proj conv epilogue (2 s_nop 0 pads kept for trans hazards)
# speedup vs baseline: 1.0037x; 1.0037x over previous
.LBB0_706:
	s_or_b64 exec, exec, s[0:1]
	v_fmamk_f32 v146, v202, 0x3a800000, v193
	v_rsq_f32_e32 v146, v146
	s_nop 0
	v_pk_mul_f32 v[150:151], v[140:141], v[146:147] op_sel_hi:[1,0]
	v_pk_mul_f32 v[140:141], v[142:143], v[146:147] op_sel_hi:[1,0]
	v_pk_mul_f32 v[154:155], v[132:133], v[146:147] op_sel_hi:[1,0]
	v_pk_mul_f32 v[132:133], v[138:139], v[146:147] op_sel_hi:[1,0]
	v_mov_b32_dpp v142, v182 row_ror:2 row_mask:0xf bank_mask:0xf
	v_mov_b32_dpp v143, v183 row_ror:2 row_mask:0xf bank_mask:0xf
	v_mov_b32_dpp v138, v182 row_ror:1 row_mask:0xf bank_mask:0xf
	v_mov_b32_dpp v139, v183 row_ror:1 row_mask:0xf bank_mask:0xf
	v_mov_b32_dpp v142, v150 row_shr:2 row_mask:0xf bank_mask:0xf
	v_mov_b32_dpp v143, v151 row_shr:2 row_mask:0xf bank_mask:0xf
	v_mov_b32_dpp v138, v150 row_shr:1 row_mask:0xf bank_mask:0xf
	v_mov_b32_dpp v139, v151 row_shr:1 row_mask:0xf bank_mask:0xf
	v_pk_fma_f32 v[142:143], v[80:81], v[142:143], v[84:85]
	v_pk_fma_f32 v[138:139], v[88:89], v[138:139], v[142:143]
	v_mov_b32_dpp v182, v156 row_ror:2 row_mask:0xf bank_mask:0xf
	v_mov_b32_dpp v183, v157 row_ror:2 row_mask:0xf bank_mask:0xf
	v_pk_fma_f32 v[138:139], v[92:93], v[150:151], v[138:139]
	v_mov_b32_dpp v158, v156 row_ror:1 row_mask:0xf bank_mask:0xf
	v_mov_b32_dpp v159, v157 row_ror:1 row_mask:0xf bank_mask:0xf
	v_mov_b32_dpp v182, v140 row_shr:2 row_mask:0xf bank_mask:0xf
	v_mov_b32_dpp v183, v141 row_shr:2 row_mask:0xf bank_mask:0xf
	v_pk_mul_f32 v[142:143], v[138:139], v[138:139]
	v_mov_b32_dpp v158, v140 row_shr:1 row_mask:0xf bank_mask:0xf
	v_mov_b32_dpp v159, v141 row_shr:1 row_mask:0xf bank_mask:0xf
	v_pk_fma_f32 v[156:157], v[82:83], v[182:183], v[86:87]
	v_pk_fma_f32 v[142:143], v[142:143], s[54:55], 1.0 op_sel_hi:[1,0,0]
	v_pk_fma_f32 v[156:157], v[90:91], v[158:159], v[156:157]
	v_pk_mul_f32 v[142:143], v[138:139], v[142:143]
	v_pk_fma_f32 v[156:157], v[94:95], v[140:141], v[156:157]
	v_pk_mul_f32 v[142:143], v[142:143], s[56:57] op_sel_hi:[1,0]
	v_pk_mul_f32 v[158:159], v[156:157], v[156:157]
	v_exp_f32_e32 v142, v142
	v_exp_f32_e32 v143, v143
	v_pk_fma_f32 v[158:159], v[158:159], s[54:55], 1.0 op_sel_hi:[1,0,0]
	v_pk_mul_f32 v[136:137], v[136:137], v[146:147] op_sel_hi:[1,0]
	v_pk_mul_f32 v[158:159], v[156:157], v[158:159]
	v_pk_add_f32 v[142:143], v[142:143], 1.0 op_sel_hi:[1,0]
	v_pk_mul_f32 v[158:159], v[158:159], s[56:57] op_sel_hi:[1,0]
	v_rcp_f32_e32 v142, v142
	v_exp_f32_e32 v158, v158
	v_exp_f32_e32 v159, v159
	v_rcp_f32_e32 v143, v143
	v_pk_mul_f32 v[128:129], v[128:129], v[146:147] op_sel_hi:[1,0]
	v_pk_mul_f32 v[134:135], v[134:135], v[146:147] op_sel_hi:[1,0]
	v_pk_add_f32 v[158:159], v[158:159], 1.0 op_sel_hi:[1,0]
	v_pk_mul_f32 v[138:139], v[138:139], v[142:143]
	v_rcp_f32_e32 v158, v158
	v_rcp_f32_e32 v159, v159
	v_pk_mul_f32 v[138:139], v[154:155], v[138:139]
	v_pk_mul_f32 v[130:131], v[130:131], v[146:147] op_sel_hi:[1,0]
	v_mov_b32_dpp v154, v152 row_ror:2 row_mask:0xf bank_mask:0xf
	v_mov_b32_dpp v155, v153 row_ror:2 row_mask:0xf bank_mask:0xf
	v_pk_mul_f32 v[142:143], v[156:157], v[158:159]
	v_mov_b32_dpp v154, v136 row_shr:2 row_mask:0xf bank_mask:0xf
	v_mov_b32_dpp v155, v137 row_shr:2 row_mask:0xf bank_mask:0xf
	v_mov_b32_dpp v146, v152 row_ror:1 row_mask:0xf bank_mask:0xf
	v_mov_b32_dpp v147, v153 row_ror:1 row_mask:0xf bank_mask:0xf
	v_pk_fma_f32 v[152:153], v[60:61], v[154:155], v[68:69]
	v_mov_b32_dpp v156, v148 row_ror:2 row_mask:0xf bank_mask:0xf
	v_mov_b32_dpp v157, v149 row_ror:2 row_mask:0xf bank_mask:0xf
	v_mov_b32_dpp v146, v136 row_shr:1 row_mask:0xf bank_mask:0xf
	v_mov_b32_dpp v147, v137 row_shr:1 row_mask:0xf bank_mask:0xf
	v_mov_b32_dpp v154, v148 row_ror:1 row_mask:0xf bank_mask:0xf
	v_mov_b32_dpp v155, v149 row_ror:1 row_mask:0xf bank_mask:0xf
	v_mov_b32_dpp v156, v132 row_shr:2 row_mask:0xf bank_mask:0xf
	v_mov_b32_dpp v157, v133 row_shr:2 row_mask:0xf bank_mask:0xf
	v_pk_fma_f32 v[146:147], v[72:73], v[146:147], v[152:153]
	v_mov_b32_dpp v154, v132 row_shr:1 row_mask:0xf bank_mask:0xf
	v_mov_b32_dpp v155, v133 row_shr:1 row_mask:0xf bank_mask:0xf
	v_pk_fma_f32 v[148:149], v[62:63], v[156:157], v[70:71]
	v_pk_fma_f32 v[146:147], v[76:77], v[136:137], v[146:147]
	v_pk_fma_f32 v[148:149], v[74:75], v[154:155], v[148:149]
	v_pk_mul_f32 v[152:153], v[146:147], v[146:147]
	v_pk_fma_f32 v[148:149], v[78:79], v[132:133], v[148:149]
	v_pk_fma_f32 v[152:153], v[152:153], s[54:55], 1.0 op_sel_hi:[1,0,0]
	v_pk_mul_f32 v[154:155], v[148:149], v[148:149]
	v_pk_mul_f32 v[152:153], v[146:147], v[152:153]
	v_pk_fma_f32 v[154:155], v[154:155], s[54:55], 1.0 op_sel_hi:[1,0,0]
	v_pk_mul_f32 v[152:153], v[152:153], s[56:57] op_sel_hi:[1,0]
	v_pk_mul_f32 v[154:155], v[148:149], v[154:155]
	v_exp_f32_e32 v152, v152
	v_exp_f32_e32 v153, v153
	v_pk_mul_f32 v[154:155], v[154:155], s[56:57] op_sel_hi:[1,0]
	v_pk_mul_f32 v[134:135], v[134:135], v[142:143]
	v_exp_f32_e32 v154, v154
	v_exp_f32_e32 v155, v155
	v_pk_add_f32 v[152:153], v[152:153], 1.0 op_sel_hi:[1,0]
	v_pk_add_f32 v[154:155], v[154:155], 1.0 op_sel_hi:[1,0]
	v_rcp_f32_e32 v152, v152
	v_rcp_f32_e32 v153, v153
	v_rcp_f32_e32 v154, v154
	v_rcp_f32_e32 v155, v155
	v_pk_mul_f32 v[142:143], v[146:147], v[152:153]
	s_nop 0
	v_pk_mul_f32 v[128:129], v[128:129], v[142:143]
	v_pk_mul_f32 v[142:143], v[148:149], v[154:155]
	v_cvt_pk_bf16_f32 v146, v138, v139
	v_cvt_pk_bf16_f32 v147, v134, v135
	v_cvt_pk_bf16_f32 v148, v128, v129
	v_mov_b64_e32 v[128:129], s[28:29]
	v_pk_mul_f32 v[130:131], v[130:131], v[142:143]
	v_or_b32_e32 v142, 16, v198
	v_cvt_pk_bf16_f32 v149, v130, v131
	v_fmamk_f32 v130, v201, 0x3a800000, v193
	v_rsq_f32_e32 v130, v130
	v_mad_i64_i32 v[134:135], s[0:1], v142, s72, v[128:129]
	v_lshl_add_u64 v[134:135], v[134:135], 0, v[144:145]
	global_store_dwordx4 v[134:135], v[146:149], off
	v_pk_mul_f32 v[134:135], v[124:125], v[130:131] op_sel_hi:[1,0]
	v_pk_mul_f32 v[124:125], v[116:117], v[130:131] op_sel_hi:[1,0]
	v_pk_mul_f32 v[116:117], v[126:127], v[130:131] op_sel_hi:[1,0]
	v_pk_mul_f32 v[138:139], v[112:113], v[130:131] op_sel_hi:[1,0]
	v_pk_mul_f32 v[112:113], v[122:123], v[130:131] op_sel_hi:[1,0]
	v_mov_b32_dpp v126, v150 row_ror:2 row_mask:0xf bank_mask:0xf
	v_mov_b32_dpp v127, v151 row_ror:2 row_mask:0xf bank_mask:0xf
	v_mov_b32_dpp v122, v150 row_ror:1 row_mask:0xf bank_mask:0xf
	v_mov_b32_dpp v123, v151 row_ror:1 row_mask:0xf bank_mask:0xf
	v_mov_b32_dpp v126, v134 row_shr:2 row_mask:0xf bank_mask:0xf
	v_mov_b32_dpp v127, v135 row_shr:2 row_mask:0xf bank_mask:0xf
	v_mov_b32_dpp v146, v140 row_ror:2 row_mask:0xf bank_mask:0xf
	v_mov_b32_dpp v147, v141 row_ror:2 row_mask:0xf bank_mask:0xf
	v_mov_b32_dpp v122, v134 row_shr:1 row_mask:0xf bank_mask:0xf
	v_mov_b32_dpp v123, v135 row_shr:1 row_mask:0xf bank_mask:0xf
	v_pk_fma_f32 v[126:127], v[80:81], v[126:127], v[84:85]
	v_mov_b32_dpp v142, v140 row_ror:1 row_mask:0xf bank_mask:0xf
	v_mov_b32_dpp v143, v141 row_ror:1 row_mask:0xf bank_mask:0xf
	v_mov_b32_dpp v146, v116 row_shr:2 row_mask:0xf bank_mask:0xf
	v_mov_b32_dpp v147, v117 row_shr:2 row_mask:0xf bank_mask:0xf
	v_pk_fma_f32 v[122:123], v[88:89], v[122:123], v[126:127]
	v_mov_b32_dpp v142, v116 row_shr:1 row_mask:0xf bank_mask:0xf
	v_mov_b32_dpp v143, v117 row_shr:1 row_mask:0xf bank_mask:0xf
	v_pk_fma_f32 v[140:141], v[82:83], v[146:147], v[86:87]
	v_pk_fma_f32 v[122:123], v[92:93], v[134:135], v[122:123]
	v_pk_fma_f32 v[140:141], v[90:91], v[142:143], v[140:141]
	v_pk_mul_f32 v[126:127], v[122:123], v[122:123]
	v_pk_fma_f32 v[140:141], v[94:95], v[116:117], v[140:141]
	v_pk_fma_f32 v[126:127], v[126:127], s[54:55], 1.0 op_sel_hi:[1,0,0]
	v_pk_mul_f32 v[142:143], v[140:141], v[140:141]
	v_pk_mul_f32 v[126:127], v[122:123], v[126:127]
	v_pk_fma_f32 v[142:143], v[142:143], s[54:55], 1.0 op_sel_hi:[1,0,0]
	v_pk_mul_f32 v[126:127], v[126:127], s[56:57] op_sel_hi:[1,0]
	v_pk_mul_f32 v[142:143], v[140:141], v[142:143]
	v_exp_f32_e32 v126, v126
	v_exp_f32_e32 v127, v127
	v_pk_mul_f32 v[142:143], v[142:143], s[56:57] op_sel_hi:[1,0]
	v_pk_mul_f32 v[120:121], v[120:121], v[130:131] op_sel_hi:[1,0]
	v_exp_f32_e32 v142, v142
	v_exp_f32_e32 v143, v143
	v_pk_add_f32 v[126:127], v[126:127], 1.0 op_sel_hi:[1,0]
	v_pk_mul_f32 v[118:119], v[118:119], v[130:131] op_sel_hi:[1,0]
	v_rcp_f32_e32 v126, v126
	v_rcp_f32_e32 v127, v127
	v_pk_add_f32 v[142:143], v[142:143], 1.0 op_sel_hi:[1,0]
	v_pk_mul_f32 v[114:115], v[114:115], v[130:131] op_sel_hi:[1,0]
	v_rcp_f32_e32 v142, v142
	v_rcp_f32_e32 v143, v143
	v_pk_mul_f32 v[122:123], v[122:123], v[126:127]
	v_pk_mul_f32 v[122:123], v[124:125], v[122:123]
	v_pk_mul_f32 v[124:125], v[140:141], v[142:143]
	v_mov_b32_dpp v126, v136 row_ror:1 row_mask:0xf bank_mask:0xf
	v_mov_b32_dpp v127, v137 row_ror:1 row_mask:0xf bank_mask:0xf
	v_mov_b32_dpp v130, v136 row_ror:2 row_mask:0xf bank_mask:0xf
	v_mov_b32_dpp v131, v137 row_ror:2 row_mask:0xf bank_mask:0xf
	v_mov_b32_dpp v140, v132 row_ror:2 row_mask:0xf bank_mask:0xf
	v_mov_b32_dpp v141, v133 row_ror:2 row_mask:0xf bank_mask:0xf
	v_mov_b32_dpp v130, v120 row_shr:2 row_mask:0xf bank_mask:0xf
	v_mov_b32_dpp v131, v121 row_shr:2 row_mask:0xf bank_mask:0xf
	v_mov_b32_dpp v136, v132 row_ror:1 row_mask:0xf bank_mask:0xf
	v_mov_b32_dpp v137, v133 row_ror:1 row_mask:0xf bank_mask:0xf
	v_mov_b32_dpp v140, v112 row_shr:2 row_mask:0xf bank_mask:0xf
	v_mov_b32_dpp v141, v113 row_shr:2 row_mask:0xf bank_mask:0xf
	v_mov_b32_dpp v126, v120 row_shr:1 row_mask:0xf bank_mask:0xf
	v_mov_b32_dpp v127, v121 row_shr:1 row_mask:0xf bank_mask:0xf
	v_pk_fma_f32 v[130:131], v[60:61], v[130:131], v[68:69]
	v_mov_b32_dpp v136, v112 row_shr:1 row_mask:0xf bank_mask:0xf
	v_mov_b32_dpp v137, v113 row_shr:1 row_mask:0xf bank_mask:0xf
	v_pk_fma_f32 v[132:133], v[62:63], v[140:141], v[70:71]
	v_pk_fma_f32 v[126:127], v[72:73], v[126:127], v[130:131]
	v_pk_fma_f32 v[132:133], v[74:75], v[136:137], v[132:133]
	v_pk_fma_f32 v[126:127], v[76:77], v[120:121], v[126:127]
	v_pk_fma_f32 v[132:133], v[78:79], v[112:113], v[132:133]
	v_pk_mul_f32 v[130:131], v[126:127], v[126:127]
	v_pk_mul_f32 v[136:137], v[132:133], v[132:133]
	v_pk_fma_f32 v[130:131], v[130:131], s[54:55], 1.0 op_sel_hi:[1,0,0]
	v_pk_fma_f32 v[136:137], v[136:137], s[54:55], 1.0 op_sel_hi:[1,0,0]
	v_pk_mul_f32 v[130:131], v[126:127], v[130:131]
	v_pk_mul_f32 v[136:137], v[132:133], v[136:137]
	v_pk_mul_f32 v[130:131], v[130:131], s[56:57] op_sel_hi:[1,0]
	v_pk_mul_f32 v[136:137], v[136:137], s[56:57] op_sel_hi:[1,0]
	v_exp_f32_e32 v130, v130
	v_exp_f32_e32 v131, v131
	v_exp_f32_e32 v136, v136
	v_exp_f32_e32 v137, v137
	v_pk_mul_f32 v[118:119], v[118:119], v[124:125]
	v_pk_add_f32 v[130:131], v[130:131], 1.0 op_sel_hi:[1,0]
	v_cvt_pk_bf16_f32 v122, v122, v123
	v_pk_add_f32 v[136:137], v[136:137], 1.0 op_sel_hi:[1,0]
	v_rcp_f32_e32 v130, v130
	v_rcp_f32_e32 v131, v131
	v_rcp_f32_e32 v136, v136
	v_rcp_f32_e32 v137, v137
	v_cvt_pk_bf16_f32 v123, v118, v119
	v_pk_mul_f32 v[124:125], v[126:127], v[130:131]
	v_pk_mul_f32 v[126:127], v[132:133], v[136:137]
	v_pk_mul_f32 v[124:125], v[138:139], v[124:125]
	v_pk_mul_f32 v[114:115], v[114:115], v[126:127]
	v_cvt_pk_bf16_f32 v124, v124, v125
	v_or_b32_e32 v126, 32, v198
	v_cvt_pk_bf16_f32 v125, v114, v115
	v_fmamk_f32 v114, v200, 0x3a800000, v193
	v_rsq_f32_e32 v114, v114
	v_mad_i64_i32 v[118:119], s[0:1], v126, s72, v[128:129]
	v_lshl_add_u64 v[118:119], v[118:119], 0, v[144:145]
	global_store_dwordx4 v[118:119], v[122:125], off
	v_pk_mul_f32 v[118:119], v[100:101], v[114:115] op_sel_hi:[1,0]
	v_pk_mul_f32 v[100:101], v[110:111], v[114:115] op_sel_hi:[1,0]
	v_pk_mul_f32 v[108:109], v[108:109], v[114:115] op_sel_hi:[1,0]
	v_pk_mul_f32 v[122:123], v[96:97], v[114:115] op_sel_hi:[1,0]
	v_pk_mul_f32 v[96:97], v[106:107], v[114:115] op_sel_hi:[1,0]
	v_mov_b32_dpp v110, v134 row_ror:2 row_mask:0xf bank_mask:0xf
	v_mov_b32_dpp v111, v135 row_ror:2 row_mask:0xf bank_mask:0xf
	v_mov_b32_dpp v126, v116 row_ror:2 row_mask:0xf bank_mask:0xf
	v_mov_b32_dpp v127, v117 row_ror:2 row_mask:0xf bank_mask:0xf
	v_mov_b32_dpp v106, v134 row_ror:1 row_mask:0xf bank_mask:0xf
	v_mov_b32_dpp v107, v135 row_ror:1 row_mask:0xf bank_mask:0xf
	v_mov_b32_dpp v110, v108 row_shr:2 row_mask:0xf bank_mask:0xf
	v_mov_b32_dpp v111, v109 row_shr:2 row_mask:0xf bank_mask:0xf
	v_mov_b32_dpp v124, v116 row_ror:1 row_mask:0xf bank_mask:0xf
	v_mov_b32_dpp v125, v117 row_ror:1 row_mask:0xf bank_mask:0xf
	v_mov_b32_dpp v126, v100 row_shr:2 row_mask:0xf bank_mask:0xf
	v_mov_b32_dpp v127, v101 row_shr:2 row_mask:0xf bank_mask:0xf
	v_mov_b32_dpp v106, v108 row_shr:1 row_mask:0xf bank_mask:0xf
	v_mov_b32_dpp v107, v109 row_shr:1 row_mask:0xf bank_mask:0xf
	v_pk_fma_f32 v[110:111], v[80:81], v[110:111], v[84:85]
	v_mov_b32_dpp v124, v100 row_shr:1 row_mask:0xf bank_mask:0xf
	v_mov_b32_dpp v125, v101 row_shr:1 row_mask:0xf bank_mask:0xf
	v_pk_fma_f32 v[116:117], v[82:83], v[126:127], v[86:87]
	v_pk_fma_f32 v[106:107], v[88:89], v[106:107], v[110:111]
	v_pk_fma_f32 v[116:117], v[90:91], v[124:125], v[116:117]
	v_pk_fma_f32 v[106:107], v[92:93], v[108:109], v[106:107]
	v_pk_fma_f32 v[116:117], v[94:95], v[100:101], v[116:117]
	v_pk_mul_f32 v[110:111], v[106:107], v[106:107]
	v_pk_mul_f32 v[124:125], v[116:117], v[116:117]
	v_pk_fma_f32 v[110:111], v[110:111], s[54:55], 1.0 op_sel_hi:[1,0,0]
	v_pk_fma_f32 v[124:125], v[124:125], s[54:55], 1.0 op_sel_hi:[1,0,0]
	v_pk_mul_f32 v[110:111], v[106:107], v[110:111]
	v_pk_mul_f32 v[124:125], v[116:117], v[124:125]
	v_pk_mul_f32 v[110:111], v[110:111], s[56:57] op_sel_hi:[1,0]
	v_pk_mul_f32 v[124:125], v[124:125], s[56:57] op_sel_hi:[1,0]
	v_exp_f32_e32 v110, v110
	v_exp_f32_e32 v111, v111
	v_exp_f32_e32 v124, v124
	v_exp_f32_e32 v125, v125
	v_pk_mul_f32 v[104:105], v[104:105], v[114:115] op_sel_hi:[1,0]
	v_pk_add_f32 v[110:111], v[110:111], 1.0 op_sel_hi:[1,0]
	v_pk_mul_f32 v[102:103], v[102:103], v[114:115] op_sel_hi:[1,0]
	v_pk_add_f32 v[124:125], v[124:125], 1.0 op_sel_hi:[1,0]
	v_rcp_f32_e32 v110, v110
	v_rcp_f32_e32 v111, v111
	v_rcp_f32_e32 v124, v124
	v_rcp_f32_e32 v125, v125
	v_pk_mul_f32 v[98:99], v[98:99], v[114:115] op_sel_hi:[1,0]
	v_pk_mul_f32 v[106:107], v[106:107], v[110:111]
	v_pk_mul_f32 v[110:111], v[116:117], v[124:125]
	v_mov_b32_dpp v114, v120 row_ror:1 row_mask:0xf bank_mask:0xf
	v_mov_b32_dpp v115, v121 row_ror:1 row_mask:0xf bank_mask:0xf
	v_mov_b32_dpp v116, v120 row_ror:2 row_mask:0xf bank_mask:0xf
	v_mov_b32_dpp v117, v121 row_ror:2 row_mask:0xf bank_mask:0xf
	v_pk_mul_f32 v[106:107], v[118:119], v[106:107]
	v_mov_b32_dpp v116, v104 row_shr:2 row_mask:0xf bank_mask:0xf
	v_mov_b32_dpp v117, v105 row_shr:2 row_mask:0xf bank_mask:0xf
	v_mov_b32_dpp v120, v112 row_ror:2 row_mask:0xf bank_mask:0xf
	v_mov_b32_dpp v121, v113 row_ror:2 row_mask:0xf bank_mask:0xf
	v_mov_b32_dpp v114, v104 row_shr:1 row_mask:0xf bank_mask:0xf
	v_mov_b32_dpp v115, v105 row_shr:1 row_mask:0xf bank_mask:0xf
	v_pk_fma_f32 v[116:117], v[60:61], v[116:117], v[68:69]
	v_mov_b32_dpp v118, v112 row_ror:1 row_mask:0xf bank_mask:0xf
	v_mov_b32_dpp v119, v113 row_ror:1 row_mask:0xf bank_mask:0xf
	v_mov_b32_dpp v120, v96 row_shr:2 row_mask:0xf bank_mask:0xf
	v_mov_b32_dpp v121, v97 row_shr:2 row_mask:0xf bank_mask:0xf
	v_pk_fma_f32 v[114:115], v[72:73], v[114:115], v[116:117]
	v_mov_b32_dpp v118, v96 row_shr:1 row_mask:0xf bank_mask:0xf
	v_mov_b32_dpp v119, v97 row_shr:1 row_mask:0xf bank_mask:0xf
	v_pk_fma_f32 v[112:113], v[62:63], v[120:121], v[70:71]
	v_pk_fma_f32 v[114:115], v[76:77], v[104:105], v[114:115]
	v_pk_fma_f32 v[112:113], v[74:75], v[118:119], v[112:113]
	v_pk_mul_f32 v[116:117], v[114:115], v[114:115]
	v_pk_fma_f32 v[112:113], v[78:79], v[96:97], v[112:113]
	v_pk_fma_f32 v[116:117], v[116:117], s[54:55], 1.0 op_sel_hi:[1,0,0]
	v_pk_mul_f32 v[118:119], v[112:113], v[112:113]
	v_pk_mul_f32 v[116:117], v[114:115], v[116:117]
	v_pk_fma_f32 v[118:119], v[118:119], s[54:55], 1.0 op_sel_hi:[1,0,0]
	v_pk_mul_f32 v[116:117], v[116:117], s[56:57] op_sel_hi:[1,0]
	v_pk_mul_f32 v[118:119], v[112:113], v[118:119]
	v_exp_f32_e32 v116, v116
	v_exp_f32_e32 v117, v117
	v_pk_mul_f32 v[118:119], v[118:119], s[56:57] op_sel_hi:[1,0]
	v_pk_mul_f32 v[102:103], v[102:103], v[110:111]
	v_exp_f32_e32 v118, v118
	v_exp_f32_e32 v119, v119
	v_pk_add_f32 v[116:117], v[116:117], 1.0 op_sel_hi:[1,0]
	v_pk_add_f32 v[118:119], v[118:119], 1.0 op_sel_hi:[1,0]
	v_rcp_f32_e32 v116, v116
	v_rcp_f32_e32 v117, v117
	v_rcp_f32_e32 v118, v118
	v_rcp_f32_e32 v119, v119
	v_pk_mul_f32 v[110:111], v[114:115], v[116:117]
	s_nop 0
	v_pk_mul_f32 v[114:115], v[122:123], v[110:111]
	v_pk_mul_f32 v[110:111], v[112:113], v[118:119]
	v_or_b32_e32 v116, 48, v198
	v_pk_mul_f32 v[98:99], v[98:99], v[110:111]
	v_cvt_pk_bf16_f32 v110, v106, v107
	v_cvt_pk_bf16_f32 v111, v102, v103
	v_cvt_pk_bf16_f32 v112, v114, v115
	s_nop 0
	v_cvt_pk_bf16_f32 v113, v98, v99
	v_mad_i64_i32 v[98:99], s[0:1], v116, s72, v[128:129]
	v_lshl_add_u64 v[98:99], v[98:99], 0, v[144:145]
	global_store_dwordx4 v[98:99], v[110:113], off
	s_and_saveexec_b64 s[0:1], s[6:7]
	s_cbranch_execz .LBB0_708
	v_readlane_b32 s18, v254, 35
	v_readlane_b32 s19, v254, 36
	v_lshl_add_u64 v[102:103], s[68:69], 0, v[170:171]
	v_cvt_pk_bf16_f32 v98, v108, v109
	v_cvt_pk_bf16_f32 v99, v100, v101
	v_cvt_pk_bf16_f32 v100, v104, v105
	v_cvt_pk_bf16_f32 v101, v96, v97
	s_nop 0
	v_mov_b64_e32 v[96:97], s[18:19]
	v_mad_u64_u32 v[96:97], s[18:19], v102, s72, v[96:97]
	v_mad_i32_i24 v97, v103, s72, v97
	v_lshl_add_u64 v[96:97], v[180:181], 1, v[96:97]
	global_store_dwordx4 v[96:97], v[98:101], off

.LBB0_710:
	s_or_b64 exec, exec, s[24:25]
	v_fmamk_f32 v50, v197, 0x3a800000, v193
	v_rsq_f32_e32 v50, v50
	s_nop 0
	v_pk_mul_f32 v[54:55], v[44:45], v[50:51] op_sel_hi:[1,0]
	v_pk_mul_f32 v[58:59], v[36:37], v[50:51] op_sel_hi:[1,0]
	v_pk_mul_f32 v[44:45], v[46:47], v[50:51] op_sel_hi:[1,0]
	v_pk_mul_f32 v[36:37], v[42:43], v[50:51] op_sel_hi:[1,0]
	v_mov_b32_dpp v42, v64 row_ror:1 row_mask:0xf bank_mask:0xf
	v_mov_b32_dpp v43, v65 row_ror:1 row_mask:0xf bank_mask:0xf
	v_mov_b32_dpp v46, v64 row_ror:2 row_mask:0xf bank_mask:0xf
	v_mov_b32_dpp v47, v65 row_ror:2 row_mask:0xf bank_mask:0xf
	v_mov_b32_dpp v66, v52 row_ror:2 row_mask:0xf bank_mask:0xf
	v_mov_b32_dpp v67, v53 row_ror:2 row_mask:0xf bank_mask:0xf
	v_mov_b32_dpp v46, v54 row_shr:2 row_mask:0xf bank_mask:0xf
	v_mov_b32_dpp v47, v55 row_shr:2 row_mask:0xf bank_mask:0xf
	v_mov_b32_dpp v64, v52 row_ror:1 row_mask:0xf bank_mask:0xf
	v_mov_b32_dpp v65, v53 row_ror:1 row_mask:0xf bank_mask:0xf
	v_mov_b32_dpp v66, v44 row_shr:2 row_mask:0xf bank_mask:0xf
	v_mov_b32_dpp v67, v45 row_shr:2 row_mask:0xf bank_mask:0xf
	v_mov_b32_dpp v42, v54 row_shr:1 row_mask:0xf bank_mask:0xf
	v_mov_b32_dpp v43, v55 row_shr:1 row_mask:0xf bank_mask:0xf
	v_pk_fma_f32 v[46:47], v[80:81], v[46:47], v[84:85]
	v_mov_b32_dpp v64, v44 row_shr:1 row_mask:0xf bank_mask:0xf
	v_mov_b32_dpp v65, v45 row_shr:1 row_mask:0xf bank_mask:0xf
	v_pk_fma_f32 v[52:53], v[82:83], v[66:67], v[86:87]
	v_pk_fma_f32 v[42:43], v[88:89], v[42:43], v[46:47]
	v_pk_fma_f32 v[52:53], v[90:91], v[64:65], v[52:53]
	v_pk_fma_f32 v[42:43], v[92:93], v[54:55], v[42:43]
	v_pk_fma_f32 v[52:53], v[94:95], v[44:45], v[52:53]
	v_pk_mul_f32 v[46:47], v[42:43], v[42:43]
	v_pk_mul_f32 v[64:65], v[52:53], v[52:53]
	v_pk_fma_f32 v[46:47], v[46:47], s[54:55], 1.0 op_sel_hi:[1,0,0]
	v_pk_fma_f32 v[64:65], v[64:65], s[54:55], 1.0 op_sel_hi:[1,0,0]
	v_pk_mul_f32 v[46:47], v[42:43], v[46:47]
	v_pk_mul_f32 v[64:65], v[52:53], v[64:65]
	v_pk_mul_f32 v[46:47], v[46:47], s[56:57] op_sel_hi:[1,0]
	v_pk_mul_f32 v[64:65], v[64:65], s[56:57] op_sel_hi:[1,0]
	v_exp_f32_e32 v46, v46
	v_exp_f32_e32 v47, v47
	v_exp_f32_e32 v64, v64
	v_exp_f32_e32 v65, v65
	v_pk_mul_f32 v[40:41], v[40:41], v[50:51] op_sel_hi:[1,0]
	v_pk_add_f32 v[46:47], v[46:47], 1.0 op_sel_hi:[1,0]
	v_pk_mul_f32 v[32:33], v[32:33], v[50:51] op_sel_hi:[1,0]
	v_pk_add_f32 v[64:65], v[64:65], 1.0 op_sel_hi:[1,0]
	v_rcp_f32_e32 v46, v46
	v_rcp_f32_e32 v47, v47
	v_rcp_f32_e32 v64, v64
	v_rcp_f32_e32 v65, v65
	v_pk_mul_f32 v[38:39], v[38:39], v[50:51] op_sel_hi:[1,0]
	v_pk_mul_f32 v[42:43], v[42:43], v[46:47]
	v_pk_mul_f32 v[34:35], v[34:35], v[50:51] op_sel_hi:[1,0]
	v_pk_mul_f32 v[46:47], v[52:53], v[64:65]
	v_pk_mul_f32 v[42:43], v[58:59], v[42:43]
	v_mov_b32_dpp v52, v56 row_ror:2 row_mask:0xf bank_mask:0xf
	v_mov_b32_dpp v53, v57 row_ror:2 row_mask:0xf bank_mask:0xf
	v_mov_b32_dpp v50, v56 row_ror:1 row_mask:0xf bank_mask:0xf
	v_mov_b32_dpp v51, v57 row_ror:1 row_mask:0xf bank_mask:0xf
	v_mov_b32_dpp v52, v40 row_shr:2 row_mask:0xf bank_mask:0xf
	v_mov_b32_dpp v53, v41 row_shr:2 row_mask:0xf bank_mask:0xf
	v_mov_b32_dpp v58, v48 row_ror:2 row_mask:0xf bank_mask:0xf
	v_mov_b32_dpp v59, v49 row_ror:2 row_mask:0xf bank_mask:0xf
	v_mov_b32_dpp v50, v40 row_shr:1 row_mask:0xf bank_mask:0xf
	v_mov_b32_dpp v51, v41 row_shr:1 row_mask:0xf bank_mask:0xf
	v_pk_fma_f32 v[52:53], v[60:61], v[52:53], v[68:69]
	v_mov_b32_dpp v56, v48 row_ror:1 row_mask:0xf bank_mask:0xf
	v_mov_b32_dpp v57, v49 row_ror:1 row_mask:0xf bank_mask:0xf
	v_mov_b32_dpp v58, v36 row_shr:2 row_mask:0xf bank_mask:0xf
	v_mov_b32_dpp v59, v37 row_shr:2 row_mask:0xf bank_mask:0xf
	v_pk_fma_f32 v[50:51], v[72:73], v[50:51], v[52:53]
	v_mov_b32_dpp v56, v36 row_shr:1 row_mask:0xf bank_mask:0xf
	v_mov_b32_dpp v57, v37 row_shr:1 row_mask:0xf bank_mask:0xf
	v_pk_fma_f32 v[48:49], v[62:63], v[58:59], v[70:71]
	v_pk_fma_f32 v[50:51], v[76:77], v[40:41], v[50:51]
	v_pk_fma_f32 v[48:49], v[74:75], v[56:57], v[48:49]
	v_pk_mul_f32 v[52:53], v[50:51], v[50:51]
	v_pk_fma_f32 v[48:49], v[78:79], v[36:37], v[48:49]
	v_pk_fma_f32 v[52:53], v[52:53], s[54:55], 1.0 op_sel_hi:[1,0,0]
	v_pk_mul_f32 v[56:57], v[48:49], v[48:49]
	v_pk_mul_f32 v[52:53], v[50:51], v[52:53]
	v_pk_fma_f32 v[56:57], v[56:57], s[54:55], 1.0 op_sel_hi:[1,0,0]
	v_pk_mul_f32 v[52:53], v[52:53], s[56:57] op_sel_hi:[1,0]
	v_pk_mul_f32 v[56:57], v[48:49], v[56:57]
	v_exp_f32_e32 v52, v52
	v_exp_f32_e32 v53, v53
	v_pk_mul_f32 v[56:57], v[56:57], s[56:57] op_sel_hi:[1,0]
	v_pk_mul_f32 v[38:39], v[38:39], v[46:47]
	v_exp_f32_e32 v56, v56
	v_exp_f32_e32 v57, v57
	v_pk_add_f32 v[52:53], v[52:53], 1.0 op_sel_hi:[1,0]
	v_pk_add_f32 v[56:57], v[56:57], 1.0 op_sel_hi:[1,0]
	v_rcp_f32_e32 v52, v52
	v_rcp_f32_e32 v53, v53
	v_rcp_f32_e32 v56, v56
	v_rcp_f32_e32 v57, v57
	v_pk_mul_f32 v[46:47], v[50:51], v[52:53]
	s_nop 0
	v_pk_mul_f32 v[32:33], v[32:33], v[46:47]
	v_pk_mul_f32 v[46:47], v[48:49], v[56:57]
	v_or_b32_e32 v50, 16, v100
	v_pk_mul_f32 v[34:35], v[34:35], v[46:47]
	v_cvt_pk_bf16_f32 v46, v42, v43
	v_cvt_pk_bf16_f32 v47, v38, v39
	v_cvt_pk_bf16_f32 v48, v32, v33
	v_mov_b64_e32 v[32:33], s[28:29]
	v_cvt_pk_bf16_f32 v49, v34, v35
	v_fmamk_f32 v34, v196, 0x3a800000, v193
	v_rsq_f32_e32 v34, v34
	v_mad_i64_i32 v[38:39], s[0:1], v50, s72, v[32:33]
	v_lshl_add_u64 v[38:39], v[38:39], 0, v[144:145]
	global_store_dwordx4 v[38:39], v[46:49], off
	v_pk_mul_f32 v[38:39], v[28:29], v[34:35] op_sel_hi:[1,0]
	v_pk_mul_f32 v[28:29], v[20:21], v[34:35] op_sel_hi:[1,0]
	v_pk_mul_f32 v[20:21], v[30:31], v[34:35] op_sel_hi:[1,0]
	v_pk_mul_f32 v[42:43], v[16:17], v[34:35] op_sel_hi:[1,0]
	v_pk_mul_f32 v[16:17], v[26:27], v[34:35] op_sel_hi:[1,0]
	v_mov_b32_dpp v30, v54 row_ror:2 row_mask:0xf bank_mask:0xf
	v_mov_b32_dpp v31, v55 row_ror:2 row_mask:0xf bank_mask:0xf
	v_mov_b32_dpp v26, v54 row_ror:1 row_mask:0xf bank_mask:0xf
	v_mov_b32_dpp v27, v55 row_ror:1 row_mask:0xf bank_mask:0xf
	v_mov_b32_dpp v30, v38 row_shr:2 row_mask:0xf bank_mask:0xf
	v_mov_b32_dpp v31, v39 row_shr:2 row_mask:0xf bank_mask:0xf
	v_mov_b32_dpp v48, v44 row_ror:2 row_mask:0xf bank_mask:0xf
	v_mov_b32_dpp v49, v45 row_ror:2 row_mask:0xf bank_mask:0xf
	v_mov_b32_dpp v26, v38 row_shr:1 row_mask:0xf bank_mask:0xf
	v_mov_b32_dpp v27, v39 row_shr:1 row_mask:0xf bank_mask:0xf
	v_pk_fma_f32 v[30:31], v[80:81], v[30:31], v[84:85]
	v_mov_b32_dpp v46, v44 row_ror:1 row_mask:0xf bank_mask:0xf
	v_mov_b32_dpp v47, v45 row_ror:1 row_mask:0xf bank_mask:0xf
	v_mov_b32_dpp v48, v20 row_shr:2 row_mask:0xf bank_mask:0xf
	v_mov_b32_dpp v49, v21 row_shr:2 row_mask:0xf bank_mask:0xf
	v_pk_fma_f32 v[26:27], v[88:89], v[26:27], v[30:31]
	v_mov_b32_dpp v46, v20 row_shr:1 row_mask:0xf bank_mask:0xf
	v_mov_b32_dpp v47, v21 row_shr:1 row_mask:0xf bank_mask:0xf
	v_pk_fma_f32 v[44:45], v[82:83], v[48:49], v[86:87]
	v_pk_fma_f32 v[26:27], v[92:93], v[38:39], v[26:27]
	v_pk_fma_f32 v[44:45], v[90:91], v[46:47], v[44:45]
	v_pk_mul_f32 v[30:31], v[26:27], v[26:27]
	v_pk_fma_f32 v[44:45], v[94:95], v[20:21], v[44:45]
	v_pk_fma_f32 v[30:31], v[30:31], s[54:55], 1.0 op_sel_hi:[1,0,0]
	v_pk_mul_f32 v[46:47], v[44:45], v[44:45]
	v_pk_mul_f32 v[30:31], v[26:27], v[30:31]
	v_pk_fma_f32 v[46:47], v[46:47], s[54:55], 1.0 op_sel_hi:[1,0,0]
	v_pk_mul_f32 v[30:31], v[30:31], s[56:57] op_sel_hi:[1,0]
	v_pk_mul_f32 v[46:47], v[44:45], v[46:47]
	v_exp_f32_e32 v30, v30
	v_exp_f32_e32 v31, v31
	v_pk_mul_f32 v[46:47], v[46:47], s[56:57] op_sel_hi:[1,0]
	v_pk_mul_f32 v[24:25], v[24:25], v[34:35] op_sel_hi:[1,0]
	v_exp_f32_e32 v46, v46
	v_exp_f32_e32 v47, v47
	v_pk_add_f32 v[30:31], v[30:31], 1.0 op_sel_hi:[1,0]
	v_pk_mul_f32 v[22:23], v[22:23], v[34:35] op_sel_hi:[1,0]
	v_rcp_f32_e32 v30, v30
	v_rcp_f32_e32 v31, v31
	v_pk_add_f32 v[46:47], v[46:47], 1.0 op_sel_hi:[1,0]
	v_pk_mul_f32 v[18:19], v[18:19], v[34:35] op_sel_hi:[1,0]
	v_rcp_f32_e32 v46, v46
	v_rcp_f32_e32 v47, v47
	v_pk_mul_f32 v[26:27], v[26:27], v[30:31]
	v_pk_mul_f32 v[26:27], v[28:29], v[26:27]
	v_pk_mul_f32 v[28:29], v[44:45], v[46:47]
	v_mov_b32_dpp v30, v40 row_ror:1 row_mask:0xf bank_mask:0xf
	v_mov_b32_dpp v31, v41 row_ror:1 row_mask:0xf bank_mask:0xf
	v_mov_b32_dpp v34, v40 row_ror:2 row_mask:0xf bank_mask:0xf
	v_mov_b32_dpp v35, v41 row_ror:2 row_mask:0xf bank_mask:0xf
	v_mov_b32_dpp v44, v36 row_ror:2 row_mask:0xf bank_mask:0xf
	v_mov_b32_dpp v45, v37 row_ror:2 row_mask:0xf bank_mask:0xf
	v_mov_b32_dpp v34, v24 row_shr:2 row_mask:0xf bank_mask:0xf
	v_mov_b32_dpp v35, v25 row_shr:2 row_mask:0xf bank_mask:0xf
	v_mov_b32_dpp v40, v36 row_ror:1 row_mask:0xf bank_mask:0xf
	v_mov_b32_dpp v41, v37 row_ror:1 row_mask:0xf bank_mask:0xf
	v_mov_b32_dpp v44, v16 row_shr:2 row_mask:0xf bank_mask:0xf
	v_mov_b32_dpp v45, v17 row_shr:2 row_mask:0xf bank_mask:0xf
	v_mov_b32_dpp v30, v24 row_shr:1 row_mask:0xf bank_mask:0xf
	v_mov_b32_dpp v31, v25 row_shr:1 row_mask:0xf bank_mask:0xf
	v_pk_fma_f32 v[34:35], v[60:61], v[34:35], v[68:69]
	v_mov_b32_dpp v40, v16 row_shr:1 row_mask:0xf bank_mask:0xf
	v_mov_b32_dpp v41, v17 row_shr:1 row_mask:0xf bank_mask:0xf
	v_pk_fma_f32 v[36:37], v[62:63], v[44:45], v[70:71]
	v_pk_fma_f32 v[30:31], v[72:73], v[30:31], v[34:35]
	v_pk_fma_f32 v[36:37], v[74:75], v[40:41], v[36:37]
	v_pk_fma_f32 v[30:31], v[76:77], v[24:25], v[30:31]
	v_pk_fma_f32 v[36:37], v[78:79], v[16:17], v[36:37]
	v_pk_mul_f32 v[34:35], v[30:31], v[30:31]
	v_pk_mul_f32 v[40:41], v[36:37], v[36:37]
	v_pk_fma_f32 v[34:35], v[34:35], s[54:55], 1.0 op_sel_hi:[1,0,0]
	v_pk_fma_f32 v[40:41], v[40:41], s[54:55], 1.0 op_sel_hi:[1,0,0]
	v_pk_mul_f32 v[34:35], v[30:31], v[34:35]
	v_pk_mul_f32 v[40:41], v[36:37], v[40:41]
	v_pk_mul_f32 v[34:35], v[34:35], s[56:57] op_sel_hi:[1,0]
	v_pk_mul_f32 v[40:41], v[40:41], s[56:57] op_sel_hi:[1,0]
	v_exp_f32_e32 v34, v34
	v_exp_f32_e32 v35, v35
	v_exp_f32_e32 v40, v40
	v_exp_f32_e32 v41, v41
	v_pk_mul_f32 v[22:23], v[22:23], v[28:29]
	v_pk_add_f32 v[34:35], v[34:35], 1.0 op_sel_hi:[1,0]
	v_cvt_pk_bf16_f32 v26, v26, v27
	v_pk_add_f32 v[40:41], v[40:41], 1.0 op_sel_hi:[1,0]
	v_rcp_f32_e32 v34, v34
	v_rcp_f32_e32 v35, v35
	v_rcp_f32_e32 v40, v40
	v_rcp_f32_e32 v41, v41
	v_cvt_pk_bf16_f32 v27, v22, v23
	v_pk_mul_f32 v[28:29], v[30:31], v[34:35]
	v_pk_mul_f32 v[30:31], v[36:37], v[40:41]
	v_pk_mul_f32 v[28:29], v[42:43], v[28:29]
	v_pk_mul_f32 v[18:19], v[18:19], v[30:31]
	v_cvt_pk_bf16_f32 v28, v28, v29
	v_or_b32_e32 v30, 32, v100
	v_cvt_pk_bf16_f32 v29, v18, v19
	v_fmamk_f32 v18, v195, 0x3a800000, v193
	v_rsq_f32_e32 v18, v18
	v_mad_i64_i32 v[22:23], s[0:1], v30, s72, v[32:33]
	v_lshl_add_u64 v[22:23], v[22:23], 0, v[144:145]
	global_store_dwordx4 v[22:23], v[26:29], off
	v_pk_mul_f32 v[22:23], v[4:5], v[18:19] op_sel_hi:[1,0]
	v_pk_mul_f32 v[4:5], v[14:15], v[18:19] op_sel_hi:[1,0]
	v_pk_mul_f32 v[12:13], v[12:13], v[18:19] op_sel_hi:[1,0]
	v_pk_mul_f32 v[26:27], v[0:1], v[18:19] op_sel_hi:[1,0]
	v_pk_mul_f32 v[0:1], v[10:11], v[18:19] op_sel_hi:[1,0]
	v_mov_b32_dpp v14, v38 row_ror:2 row_mask:0xf bank_mask:0xf
	v_mov_b32_dpp v15, v39 row_ror:2 row_mask:0xf bank_mask:0xf
	v_mov_b32_dpp v30, v20 row_ror:2 row_mask:0xf bank_mask:0xf
	v_mov_b32_dpp v31, v21 row_ror:2 row_mask:0xf bank_mask:0xf
	v_mov_b32_dpp v10, v38 row_ror:1 row_mask:0xf bank_mask:0xf
	v_mov_b32_dpp v11, v39 row_ror:1 row_mask:0xf bank_mask:0xf
	v_mov_b32_dpp v14, v12 row_shr:2 row_mask:0xf bank_mask:0xf
	v_mov_b32_dpp v15, v13 row_shr:2 row_mask:0xf bank_mask:0xf
	v_mov_b32_dpp v28, v20 row_ror:1 row_mask:0xf bank_mask:0xf
	v_mov_b32_dpp v29, v21 row_ror:1 row_mask:0xf bank_mask:0xf
	v_mov_b32_dpp v30, v4 row_shr:2 row_mask:0xf bank_mask:0xf
	v_mov_b32_dpp v31, v5 row_shr:2 row_mask:0xf bank_mask:0xf
	v_mov_b32_dpp v10, v12 row_shr:1 row_mask:0xf bank_mask:0xf
	v_mov_b32_dpp v11, v13 row_shr:1 row_mask:0xf bank_mask:0xf
	v_pk_fma_f32 v[14:15], v[80:81], v[14:15], v[84:85]
	v_mov_b32_dpp v28, v4 row_shr:1 row_mask:0xf bank_mask:0xf
	v_mov_b32_dpp v29, v5 row_shr:1 row_mask:0xf bank_mask:0xf
	v_pk_fma_f32 v[20:21], v[82:83], v[30:31], v[86:87]
	v_pk_fma_f32 v[10:11], v[88:89], v[10:11], v[14:15]
	v_pk_fma_f32 v[20:21], v[90:91], v[28:29], v[20:21]
	v_pk_fma_f32 v[10:11], v[92:93], v[12:13], v[10:11]
	v_pk_fma_f32 v[20:21], v[94:95], v[4:5], v[20:21]
	v_pk_mul_f32 v[14:15], v[10:11], v[10:11]
	v_pk_mul_f32 v[28:29], v[20:21], v[20:21]
	v_pk_fma_f32 v[14:15], v[14:15], s[54:55], 1.0 op_sel_hi:[1,0,0]
	v_pk_fma_f32 v[28:29], v[28:29], s[54:55], 1.0 op_sel_hi:[1,0,0]
	v_pk_mul_f32 v[14:15], v[10:11], v[14:15]
	v_pk_mul_f32 v[28:29], v[20:21], v[28:29]
	v_pk_mul_f32 v[14:15], v[14:15], s[56:57] op_sel_hi:[1,0]
	v_pk_mul_f32 v[28:29], v[28:29], s[56:57] op_sel_hi:[1,0]
	v_exp_f32_e32 v14, v14
	v_exp_f32_e32 v15, v15
	v_exp_f32_e32 v28, v28
	v_exp_f32_e32 v29, v29
	v_pk_mul_f32 v[8:9], v[8:9], v[18:19] op_sel_hi:[1,0]
	v_pk_add_f32 v[14:15], v[14:15], 1.0 op_sel_hi:[1,0]
	v_pk_mul_f32 v[6:7], v[6:7], v[18:19] op_sel_hi:[1,0]
	v_pk_add_f32 v[28:29], v[28:29], 1.0 op_sel_hi:[1,0]
	v_rcp_f32_e32 v14, v14
	v_rcp_f32_e32 v15, v15
	v_rcp_f32_e32 v28, v28
	v_rcp_f32_e32 v29, v29
	v_pk_mul_f32 v[2:3], v[2:3], v[18:19] op_sel_hi:[1,0]
	v_pk_mul_f32 v[10:11], v[10:11], v[14:15]
	v_pk_mul_f32 v[14:15], v[20:21], v[28:29]
	v_mov_b32_dpp v18, v24 row_ror:1 row_mask:0xf bank_mask:0xf
	v_mov_b32_dpp v19, v25 row_ror:1 row_mask:0xf bank_mask:0xf
	v_mov_b32_dpp v20, v24 row_ror:2 row_mask:0xf bank_mask:0xf
	v_mov_b32_dpp v21, v25 row_ror:2 row_mask:0xf bank_mask:0xf
	v_pk_mul_f32 v[10:11], v[22:23], v[10:11]
	v_mov_b32_dpp v20, v8 row_shr:2 row_mask:0xf bank_mask:0xf
	v_mov_b32_dpp v21, v9 row_shr:2 row_mask:0xf bank_mask:0xf
	v_mov_b32_dpp v24, v16 row_ror:2 row_mask:0xf bank_mask:0xf
	v_mov_b32_dpp v25, v17 row_ror:2 row_mask:0xf bank_mask:0xf
	v_mov_b32_dpp v18, v8 row_shr:1 row_mask:0xf bank_mask:0xf
	v_mov_b32_dpp v19, v9 row_shr:1 row_mask:0xf bank_mask:0xf
	v_pk_fma_f32 v[20:21], v[60:61], v[20:21], v[68:69]
	v_mov_b32_dpp v22, v16 row_ror:1 row_mask:0xf bank_mask:0xf
	v_mov_b32_dpp v23, v17 row_ror:1 row_mask:0xf bank_mask:0xf
	v_mov_b32_dpp v24, v0 row_shr:2 row_mask:0xf bank_mask:0xf
	v_mov_b32_dpp v25, v1 row_shr:2 row_mask:0xf bank_mask:0xf
	v_pk_fma_f32 v[18:19], v[72:73], v[18:19], v[20:21]
	v_mov_b32_dpp v22, v0 row_shr:1 row_mask:0xf bank_mask:0xf
	v_mov_b32_dpp v23, v1 row_shr:1 row_mask:0xf bank_mask:0xf
	v_pk_fma_f32 v[16:17], v[62:63], v[24:25], v[70:71]
	v_pk_fma_f32 v[18:19], v[76:77], v[8:9], v[18:19]
	v_pk_fma_f32 v[16:17], v[74:75], v[22:23], v[16:17]
	v_pk_mul_f32 v[20:21], v[18:19], v[18:19]
	v_pk_fma_f32 v[16:17], v[78:79], v[0:1], v[16:17]
	v_pk_fma_f32 v[20:21], v[20:21], s[54:55], 1.0 op_sel_hi:[1,0,0]
	v_pk_mul_f32 v[22:23], v[16:17], v[16:17]
	v_pk_mul_f32 v[20:21], v[18:19], v[20:21]
	v_pk_fma_f32 v[22:23], v[22:23], s[54:55], 1.0 op_sel_hi:[1,0,0]
	v_pk_mul_f32 v[20:21], v[20:21], s[56:57] op_sel_hi:[1,0]
	v_pk_mul_f32 v[22:23], v[16:17], v[22:23]
	v_exp_f32_e32 v20, v20
	v_exp_f32_e32 v21, v21
	v_pk_mul_f32 v[22:23], v[22:23], s[56:57] op_sel_hi:[1,0]
	v_pk_mul_f32 v[6:7], v[6:7], v[14:15]
	v_exp_f32_e32 v22, v22
	v_exp_f32_e32 v23, v23
	v_pk_add_f32 v[20:21], v[20:21], 1.0 op_sel_hi:[1,0]
	v_pk_add_f32 v[22:23], v[22:23], 1.0 op_sel_hi:[1,0]
	v_rcp_f32_e32 v20, v20
	v_rcp_f32_e32 v21, v21
	v_rcp_f32_e32 v22, v22
	v_rcp_f32_e32 v23, v23
	v_pk_mul_f32 v[14:15], v[18:19], v[20:21]
	s_nop 0
	v_pk_mul_f32 v[18:19], v[26:27], v[14:15]
	v_pk_mul_f32 v[14:15], v[16:17], v[22:23]
	v_or_b32_e32 v20, 48, v100
	v_pk_mul_f32 v[2:3], v[2:3], v[14:15]
	v_cvt_pk_bf16_f32 v14, v10, v11
	v_cvt_pk_bf16_f32 v15, v6, v7
	v_cvt_pk_bf16_f32 v16, v18, v19
	s_nop 0
	v_cvt_pk_bf16_f32 v17, v2, v3
	v_mad_i64_i32 v[2:3], s[0:1], v20, s72, v[32:33]
	v_lshl_add_u64 v[2:3], v[2:3], 0, v[144:145]
	global_store_dwordx4 v[2:3], v[14:17], off
	s_and_saveexec_b64 s[0:1], s[6:7]
	s_cbranch_execz .LBB0_712
	v_readlane_b32 s18, v254, 35
	v_readlane_b32 s19, v254, 36
	v_lshl_add_u64 v[6:7], s[66:67], 0, v[170:171]
	v_cvt_pk_bf16_f32 v2, v12, v13
	v_cvt_pk_bf16_f32 v3, v4, v5
	v_cvt_pk_bf16_f32 v4, v8, v9
	v_cvt_pk_bf16_f32 v5, v0, v1
	s_nop 0
	v_mov_b64_e32 v[0:1], s[18:19]
	v_mad_u64_u32 v[0:1], s[18:19], v6, s72, v[0:1]
	v_mad_i32_i24 v1, v7, s72, v1
	v_lshl_add_u64 v[0:1], v[180:181], 1, v[0:1]
	global_store_dwordx4 v[0:1], v[2:5], off
